# GEMM K-loop heads aligned to 64 B (placement check on top of no-setprio)
# speedup vs baseline: 1.0125x; 1.0045x over previous
; template <class Epi>
; __device__ __forceinline__ void gemm_phase(LAS unsigned char* lds, const Gemm g, const StaticOrder& S, const Epi& E, const int tid) {
;     ...
;         const bool has_next = S.next(ui + 1, nxt);
;         const char* nA = has_next ? (const char*)g.A + (size_t)nxt.pm * tstep : cA; const char* nB = has_next ? (const char*)g.Bt + (size_t)nxt.pn * tstep : cB;
;         for (int t = 0; t < nt; t += 2) {
;             const bool last = (t == nt - 2);
;             const char* a1 = cA + (size_t)(t + 1) * kstep;
;             const char* a2 = last ? nA : cA + (size_t)(t + 2) * kstep; const char* b2 = last ? nB : cB + (size_t)(t + 2) * kstep;
;             const char* a3 = a2 + kstep; const char* b3 = b2 + kstep;
;     ...
; #pragma unroll
;         for (int a = 0; a < 2; ++a)
; #pragma unroll
;             for (int b = 0; b < 2; ++b)
; #pragma unroll
;                 for (int m = 0; m < 4; ++m)
; #pragma unroll
;                     for (int n = 0; n < 2; ++n) acc[a][b][m][n] = (f32x4){0.f, 0.f, 0.f, 0.f};
;         cur = nxt; cA = nA; cB = nB; ++ui;
.LBB0_331:
	s_ashr_i32 s9, s8, 31
	v_cmp_lt_i64_e32 vcc, s[10:11], v[154:155]
	s_lshl_b64 s[10:11], s[8:9], 20
	s_add_u32 s10, s96, s10
	s_addc_u32 s11, s74, s11
	s_and_b64 s[12:13], vcc, exec
	s_cselect_b32 s9, s11, s15
	s_cselect_b32 s50, s10, s14
	s_ashr_i32 s1, s0, 31
	s_lshl_b64 s[12:13], s[0:1], 20
	s_add_u32 s12, s24, s12
	s_addc_u32 s13, s25, s13
	s_and_b64 s[22:23], vcc, exec
	s_cselect_b32 s1, s13, s19
	s_cselect_b32 s51, s12, s18
	s_add_u32 s14, s14, 0x80080
	s_addc_u32 s15, s15, 0
	s_add_u32 s52, s18, 0x100
	v_mov_b32_e32 v4, 0
	s_addc_u32 s53, s19, 0
	s_mov_b32 s54, -2
	v_mov_b32_e32 v5, v4
	v_mov_b32_e32 v6, v4
	v_mov_b32_e32 v7, v4
	v_mov_b32_e32 v8, v4
	v_mov_b32_e32 v9, v4
	v_mov_b32_e32 v10, v4
	v_mov_b32_e32 v11, v4
	v_mov_b32_e32 v24, v4
	v_mov_b32_e32 v25, v4
	v_mov_b32_e32 v26, v4
	v_mov_b32_e32 v27, v4
	v_mov_b32_e32 v20, v4
	v_mov_b32_e32 v21, v4
	v_mov_b32_e32 v22, v4
	v_mov_b32_e32 v23, v4
	v_mov_b32_e32 v40, v4
	v_mov_b32_e32 v41, v4
	v_mov_b32_e32 v42, v4
	v_mov_b32_e32 v43, v4
	v_mov_b32_e32 v36, v4
	v_mov_b32_e32 v37, v4
	v_mov_b32_e32 v38, v4
	v_mov_b32_e32 v39, v4
	v_mov_b32_e32 v56, v4
	v_mov_b32_e32 v57, v4
	v_mov_b32_e32 v58, v4
	v_mov_b32_e32 v59, v4
	v_mov_b32_e32 v52, v4
	v_mov_b32_e32 v53, v4
	v_mov_b32_e32 v54, v4
	v_mov_b32_e32 v55, v4
	v_mov_b32_e32 v16, v4
	v_mov_b32_e32 v17, v4
	v_mov_b32_e32 v18, v4
	v_mov_b32_e32 v19, v4
	v_mov_b32_e32 v12, v4
	v_mov_b32_e32 v13, v4
	v_mov_b32_e32 v14, v4
	v_mov_b32_e32 v15, v4
	v_mov_b32_e32 v32, v4
	v_mov_b32_e32 v33, v4
	v_mov_b32_e32 v34, v4
	v_mov_b32_e32 v35, v4
	v_mov_b32_e32 v28, v4
	v_mov_b32_e32 v29, v4
	v_mov_b32_e32 v30, v4
	v_mov_b32_e32 v31, v4
	v_mov_b32_e32 v48, v4
	v_mov_b32_e32 v49, v4
	v_mov_b32_e32 v50, v4
	v_mov_b32_e32 v51, v4
	v_mov_b32_e32 v44, v4
	v_mov_b32_e32 v45, v4
	v_mov_b32_e32 v46, v4
	v_mov_b32_e32 v47, v4
	v_mov_b32_e32 v64, v4
	v_mov_b32_e32 v65, v4
	v_mov_b32_e32 v66, v4
	v_mov_b32_e32 v67, v4
	v_mov_b32_e32 v60, v4
	v_mov_b32_e32 v61, v4
	v_mov_b32_e32 v62, v4
	v_mov_b32_e32 v63, v4
	v_mov_b32_e32 v72, v4
	v_mov_b32_e32 v73, v4
	v_mov_b32_e32 v74, v4
	v_mov_b32_e32 v75, v4
	v_mov_b32_e32 v68, v4
	v_mov_b32_e32 v69, v4
	v_mov_b32_e32 v70, v4
	v_mov_b32_e32 v71, v4
	v_mov_b32_e32 v88, v4
	v_mov_b32_e32 v89, v4
	v_mov_b32_e32 v90, v4
	v_mov_b32_e32 v91, v4
	v_mov_b32_e32 v84, v4
	v_mov_b32_e32 v85, v4
	v_mov_b32_e32 v86, v4
	v_mov_b32_e32 v87, v4
	v_mov_b32_e32 v104, v4
	v_mov_b32_e32 v105, v4
	v_mov_b32_e32 v106, v4
	v_mov_b32_e32 v107, v4
	v_mov_b32_e32 v100, v4
	v_mov_b32_e32 v101, v4
	v_mov_b32_e32 v102, v4
	v_mov_b32_e32 v103, v4
	v_mov_b32_e32 v120, v4
	v_mov_b32_e32 v121, v4
	v_mov_b32_e32 v122, v4
	v_mov_b32_e32 v123, v4
	v_mov_b32_e32 v116, v4
	v_mov_b32_e32 v117, v4
	v_mov_b32_e32 v118, v4
	v_mov_b32_e32 v119, v4
	v_mov_b32_e32 v80, v4
	v_mov_b32_e32 v81, v4
	v_mov_b32_e32 v82, v4
	v_mov_b32_e32 v83, v4
	v_mov_b32_e32 v76, v4
	v_mov_b32_e32 v77, v4
	v_mov_b32_e32 v78, v4
	v_mov_b32_e32 v79, v4
	v_mov_b32_e32 v96, v4
	v_mov_b32_e32 v97, v4
	v_mov_b32_e32 v98, v4
	v_mov_b32_e32 v99, v4
	v_mov_b32_e32 v92, v4
	v_mov_b32_e32 v93, v4
	v_mov_b32_e32 v94, v4
	v_mov_b32_e32 v95, v4
	v_mov_b32_e32 v112, v4
	v_mov_b32_e32 v113, v4
	v_mov_b32_e32 v114, v4
	v_mov_b32_e32 v115, v4
	v_mov_b32_e32 v108, v4
	v_mov_b32_e32 v109, v4
	v_mov_b32_e32 v110, v4
	v_mov_b32_e32 v111, v4
	v_mov_b32_e32 v128, v4
	v_mov_b32_e32 v129, v4
	v_mov_b32_e32 v130, v4
	v_mov_b32_e32 v131, v4
	v_mov_b32_e32 v124, v4
	v_mov_b32_e32 v125, v4
	v_mov_b32_e32 v126, v4
	v_mov_b32_e32 v127, v4
	.p2align	6

; template <class Epi>
; __device__ __forceinline__ void gemm_phase(LAS unsigned char* lds, const Gemm g, const StaticOrder& S, const Epi& E, const int tid) {
;     ...
;         const bool has_next = S.next(ui + 1, nxt);
;         const char* nA = has_next ? (const char*)g.A + (size_t)nxt.pm * tstep : cA; const char* nB = has_next ? (const char*)g.Bt + (size_t)nxt.pn * tstep : cB;
;         for (int t = 0; t < nt; t += 2) {
;             const bool last = (t == nt - 2);
;             const char* a1 = cA + (size_t)(t + 1) * kstep;
;             const char* a2 = last ? nA : cA + (size_t)(t + 2) * kstep; const char* b2 = last ? nB : cB + (size_t)(t + 2) * kstep;
;             const char* a3 = a2 + kstep; const char* b3 = b2 + kstep;
;     ...
; #pragma unroll
;         for (int a = 0; a < 2; ++a)
; #pragma unroll
;             for (int b = 0; b < 2; ++b)
; #pragma unroll
;                 for (int m = 0; m < 4; ++m)
; #pragma unroll
;                     for (int n = 0; n < 2; ++n) acc[a][b][m][n] = (f32x4){0.f, 0.f, 0.f, 0.f};
;         cur = nxt; cA = nA; cB = nB; ++ui;
.LBB0_593:
	s_ashr_i32 s5, s4, 31
	v_cmp_lt_i64_e32 vcc, s[6:7], v[160:161]
	s_lshl_b64 s[6:7], s[4:5], 21
	v_readlane_b32 s8, v253, 42
	v_readlane_b32 s9, v253, 43
	s_add_u32 s6, s8, s6
	s_addc_u32 s7, s9, s7
	s_and_b64 s[8:9], vcc, exec
	s_cselect_b32 s5, s7, s11
	s_cselect_b32 s50, s6, s10
	s_ashr_i32 s1, s0, 31
	s_lshl_b64 s[8:9], s[0:1], 21
	s_add_u32 s8, s22, s8
	s_addc_u32 s9, s23, s9
	v_lshl_add_u32 v166, s15, 8, v157
	v_lshl_or_b32 v168, s14, 8, v190
	s_movk_i32 s14, 0x3c00
	s_and_b64 s[18:19], vcc, exec
	v_mad_u64_u32 v[170:171], s[14:15], v166, s14, v[168:169]
	s_cselect_b32 s1, s9, s13
	s_cselect_b32 s51, s8, s12
	s_add_u32 s14, s10, 0x100080
	s_addc_u32 s15, s11, 0
	v_mov_b32_e32 v2, v3
	s_add_u32 s52, s12, 0x100
	v_mov_b32_e32 v0, v3
	v_mov_b32_e32 v1, v3
	v_mov_b64_e32 v[6:7], v[2:3]
	v_mov_b64_e32 v[10:11], v[2:3]
	v_mov_b64_e32 v[22:23], v[2:3]
	v_mov_b64_e32 v[26:27], v[2:3]
	v_mov_b64_e32 v[38:39], v[2:3]
	v_mov_b64_e32 v[42:43], v[2:3]
	v_mov_b64_e32 v[54:55], v[2:3]
	v_mov_b64_e32 v[58:59], v[2:3]
	v_mov_b64_e32 v[14:15], v[2:3]
	v_mov_b64_e32 v[18:19], v[2:3]
	v_mov_b64_e32 v[30:31], v[2:3]
	v_mov_b64_e32 v[34:35], v[2:3]
	v_mov_b64_e32 v[46:47], v[2:3]
	v_mov_b64_e32 v[50:51], v[2:3]
	v_mov_b64_e32 v[62:63], v[2:3]
	v_mov_b64_e32 v[66:67], v[2:3]
	v_mov_b64_e32 v[70:71], v[2:3]
	v_mov_b64_e32 v[74:75], v[2:3]
	v_mov_b64_e32 v[86:87], v[2:3]
	v_mov_b64_e32 v[90:91], v[2:3]
	v_mov_b64_e32 v[102:103], v[2:3]
	v_mov_b64_e32 v[106:107], v[2:3]
	v_mov_b64_e32 v[118:119], v[2:3]
	v_mov_b64_e32 v[122:123], v[2:3]
	v_mov_b64_e32 v[78:79], v[2:3]
	v_mov_b64_e32 v[82:83], v[2:3]
	v_mov_b64_e32 v[94:95], v[2:3]
	v_mov_b64_e32 v[98:99], v[2:3]
	v_mov_b64_e32 v[110:111], v[2:3]
	v_mov_b64_e32 v[114:115], v[2:3]
	v_mov_b64_e32 v[126:127], v[2:3]
	v_mov_b64_e32 v[130:131], v[2:3]
	v_lshl_add_u64 v[172:173], s[14:15], 0, v[162:163]
	v_lshl_add_u64 v[174:175], s[14:15], 0, v[164:165]
	s_addc_u32 s53, s13, 0
	s_mov_b32 s54, -2
	s_mov_b64 s[12:13], 0
	v_mov_b64_e32 v[4:5], v[0:1]
	v_mov_b64_e32 v[8:9], v[0:1]
	v_mov_b64_e32 v[20:21], v[0:1]
	v_mov_b64_e32 v[24:25], v[0:1]
	v_mov_b64_e32 v[36:37], v[0:1]
	v_mov_b64_e32 v[40:41], v[0:1]
	v_mov_b64_e32 v[52:53], v[0:1]
	v_mov_b64_e32 v[56:57], v[0:1]
	v_mov_b64_e32 v[12:13], v[0:1]
	v_mov_b64_e32 v[16:17], v[0:1]
	v_mov_b64_e32 v[28:29], v[0:1]
	v_mov_b64_e32 v[32:33], v[0:1]
	v_mov_b64_e32 v[44:45], v[0:1]
	v_mov_b64_e32 v[48:49], v[0:1]
	v_mov_b64_e32 v[60:61], v[0:1]
	v_mov_b64_e32 v[64:65], v[0:1]
	v_mov_b64_e32 v[68:69], v[0:1]
	v_mov_b64_e32 v[72:73], v[0:1]
	v_mov_b64_e32 v[84:85], v[0:1]
	v_mov_b64_e32 v[88:89], v[0:1]
	v_mov_b64_e32 v[100:101], v[0:1]
	v_mov_b64_e32 v[104:105], v[0:1]
	v_mov_b64_e32 v[116:117], v[0:1]
	v_mov_b64_e32 v[120:121], v[0:1]
	v_mov_b64_e32 v[76:77], v[0:1]
	v_mov_b64_e32 v[80:81], v[0:1]
	v_mov_b64_e32 v[92:93], v[0:1]
	v_mov_b64_e32 v[96:97], v[0:1]
	v_mov_b64_e32 v[108:109], v[0:1]
	v_mov_b64_e32 v[112:113], v[0:1]
	v_mov_b64_e32 v[124:125], v[0:1]
	v_mov_b64_e32 v[128:129], v[0:1]
	s_branch .LBB0_595
	.p2align	6

; template <class Epi>
; __device__ __forceinline__ void gemm_phase(LAS unsigned char* lds, const Gemm g, const StaticOrder& S, const Epi& E, const int tid) {
;     ...
;         const bool has_next = S.next(ui + 1, nxt);
;         const char* nA = has_next ? (const char*)g.A + (size_t)nxt.pm * tstep : cA; const char* nB = has_next ? (const char*)g.Bt + (size_t)nxt.pn * tstep : cB;
;         for (int t = 0; t < nt; t += 2) {
;             const bool last = (t == nt - 2);
;             const char* a1 = cA + (size_t)(t + 1) * kstep;
;             const char* a2 = last ? nA : cA + (size_t)(t + 2) * kstep; const char* b2 = last ? nB : cB + (size_t)(t + 2) * kstep;
;             const char* a3 = a2 + kstep; const char* b3 = b2 + kstep;
;     ...
; #pragma unroll
;         for (int a = 0; a < 2; ++a)
; #pragma unroll
;             for (int b = 0; b < 2; ++b)
; #pragma unroll
;                 for (int m = 0; m < 4; ++m)
; #pragma unroll
;                     for (int n = 0; n < 2; ++n) acc[a][b][m][n] = (f32x4){0.f, 0.f, 0.f, 0.f};
;         cur = nxt; cA = nA; cB = nB; ++ui;
.LBB0_659:
	s_ashr_i32 s7, s6, 31
	v_cmp_lt_i64_e32 vcc, s[8:9], v[160:161]
	s_lshl_b64 s[8:9], s[6:7], 20
	s_add_u32 s8, s26, s8
	s_addc_u32 s9, s27, s9
	s_and_b64 s[10:11], vcc, exec
	s_cselect_b32 s7, s9, s13
	s_cselect_b32 s52, s8, s12
	s_ashr_i32 s1, s0, 31
	s_lshl_b64 s[10:11], s[0:1], 20
	s_add_u32 s10, s20, s10
	s_addc_u32 s11, s22, s11
	s_and_b64 s[18:19], vcc, exec
	s_cselect_b32 s1, s11, s15
	s_cselect_b32 s53, s10, s14
	s_add_u32 s12, s12, 0x80080
	s_addc_u32 s13, s13, 0
	s_add_u32 s54, s14, 0x100
	v_mov_b32_e32 v4, 0
	s_addc_u32 s55, s15, 0
	s_mov_b32 s56, -2
	v_mov_b32_e32 v5, v4
	v_mov_b32_e32 v6, v4
	v_mov_b32_e32 v7, v4
	v_mov_b32_e32 v8, v4
	v_mov_b32_e32 v9, v4
	v_mov_b32_e32 v10, v4
	v_mov_b32_e32 v11, v4
	v_mov_b32_e32 v20, v4
	v_mov_b32_e32 v21, v4
	v_mov_b32_e32 v22, v4
	v_mov_b32_e32 v23, v4
	v_mov_b32_e32 v24, v4
	v_mov_b32_e32 v25, v4
	v_mov_b32_e32 v26, v4
	v_mov_b32_e32 v27, v4
	v_mov_b32_e32 v44, v4
	v_mov_b32_e32 v45, v4
	v_mov_b32_e32 v46, v4
	v_mov_b32_e32 v47, v4
	v_mov_b32_e32 v48, v4
	v_mov_b32_e32 v49, v4
	v_mov_b32_e32 v50, v4
	v_mov_b32_e32 v51, v4
	v_mov_b32_e32 v68, v4
	v_mov_b32_e32 v69, v4
	v_mov_b32_e32 v70, v4
	v_mov_b32_e32 v71, v4
	v_mov_b32_e32 v72, v4
	v_mov_b32_e32 v73, v4
	v_mov_b32_e32 v74, v4
	v_mov_b32_e32 v75, v4
	v_mov_b32_e32 v12, v4
	v_mov_b32_e32 v13, v4
	v_mov_b32_e32 v14, v4
	v_mov_b32_e32 v15, v4
	v_mov_b32_e32 v16, v4
	v_mov_b32_e32 v17, v4
	v_mov_b32_e32 v18, v4
	v_mov_b32_e32 v19, v4
	v_mov_b32_e32 v36, v4
	v_mov_b32_e32 v37, v4
	v_mov_b32_e32 v38, v4
	v_mov_b32_e32 v39, v4
	v_mov_b32_e32 v40, v4
	v_mov_b32_e32 v41, v4
	v_mov_b32_e32 v42, v4
	v_mov_b32_e32 v43, v4
	v_mov_b32_e32 v52, v4
	v_mov_b32_e32 v53, v4
	v_mov_b32_e32 v54, v4
	v_mov_b32_e32 v55, v4
	v_mov_b32_e32 v56, v4
	v_mov_b32_e32 v57, v4
	v_mov_b32_e32 v58, v4
	v_mov_b32_e32 v59, v4
	v_mov_b32_e32 v76, v4
	v_mov_b32_e32 v77, v4
	v_mov_b32_e32 v78, v4
	v_mov_b32_e32 v79, v4
	v_mov_b32_e32 v80, v4
	v_mov_b32_e32 v81, v4
	v_mov_b32_e32 v82, v4
	v_mov_b32_e32 v83, v4
	v_mov_b32_e32 v84, v4
	v_mov_b32_e32 v85, v4
	v_mov_b32_e32 v86, v4
	v_mov_b32_e32 v87, v4
	v_mov_b32_e32 v88, v4
	v_mov_b32_e32 v89, v4
	v_mov_b32_e32 v90, v4
	v_mov_b32_e32 v91, v4
	v_mov_b32_e32 v100, v4
	v_mov_b32_e32 v101, v4
	v_mov_b32_e32 v102, v4
	v_mov_b32_e32 v103, v4
	v_mov_b32_e32 v104, v4
	v_mov_b32_e32 v105, v4
	v_mov_b32_e32 v106, v4
	v_mov_b32_e32 v107, v4
	v_mov_b32_e32 v116, v4
	v_mov_b32_e32 v117, v4
	v_mov_b32_e32 v118, v4
	v_mov_b32_e32 v119, v4
	v_mov_b32_e32 v120, v4
	v_mov_b32_e32 v121, v4
	v_mov_b32_e32 v122, v4
	v_mov_b32_e32 v123, v4
	v_mov_b32_e32 v132, v4
	v_mov_b32_e32 v133, v4
	v_mov_b32_e32 v134, v4
	v_mov_b32_e32 v135, v4
	v_mov_b32_e32 v136, v4
	v_mov_b32_e32 v137, v4
	v_mov_b32_e32 v138, v4
	v_mov_b32_e32 v139, v4
	v_mov_b32_e32 v92, v4
	v_mov_b32_e32 v93, v4
	v_mov_b32_e32 v94, v4
	v_mov_b32_e32 v95, v4
	v_mov_b32_e32 v96, v4
	v_mov_b32_e32 v97, v4
	v_mov_b32_e32 v98, v4
	v_mov_b32_e32 v99, v4
	v_mov_b32_e32 v108, v4
	v_mov_b32_e32 v109, v4
	v_mov_b32_e32 v110, v4
	v_mov_b32_e32 v111, v4
	v_mov_b32_e32 v112, v4
	v_mov_b32_e32 v113, v4
	v_mov_b32_e32 v114, v4
	v_mov_b32_e32 v115, v4
	v_mov_b32_e32 v124, v4
	v_mov_b32_e32 v125, v4
	v_mov_b32_e32 v126, v4
	v_mov_b32_e32 v127, v4
	v_mov_b32_e32 v128, v4
	v_mov_b32_e32 v129, v4
	v_mov_b32_e32 v130, v4
	v_mov_b32_e32 v131, v4
	v_mov_b32_e32 v140, v4
	v_mov_b32_e32 v141, v4
	v_mov_b32_e32 v142, v4
	v_mov_b32_e32 v143, v4
	v_mov_b32_e32 v144, v4
	v_mov_b32_e32 v145, v4
	v_mov_b32_e32 v146, v4
	v_mov_b32_e32 v147, v4
	.p2align	6

; template <class Epi>
; __device__ __forceinline__ void gemm_phase(LAS unsigned char* lds, const Gemm g, const StaticOrder& S, const Epi& E, const int tid) {
;     ...
;         const bool has_next = S.next(ui + 1, nxt);
;         const char* nA = has_next ? (const char*)g.A + (size_t)nxt.pm * tstep : cA; const char* nB = has_next ? (const char*)g.Bt + (size_t)nxt.pn * tstep : cB;
;         for (int t = 0; t < nt; t += 2) {
;             const bool last = (t == nt - 2);
;             const char* a1 = cA + (size_t)(t + 1) * kstep;
;             const char* a2 = last ? nA : cA + (size_t)(t + 2) * kstep; const char* b2 = last ? nB : cB + (size_t)(t + 2) * kstep;
;             const char* a3 = a2 + kstep; const char* b3 = b2 + kstep;
;     ...
; #pragma unroll
;         for (int a = 0; a < 2; ++a)
; #pragma unroll
;             for (int b = 0; b < 2; ++b)
; #pragma unroll
;                 for (int m = 0; m < 4; ++m)
; #pragma unroll
;                     for (int n = 0; n < 2; ++n) acc[a][b][m][n] = (f32x4){0.f, 0.f, 0.f, 0.f};
;         cur = nxt; cA = nA; cB = nB; ++ui;
.LBB0_677:
	s_ashr_i32 s7, s6, 31
	v_cmp_lt_i64_e32 vcc, s[8:9], v[160:161]
	s_lshl_b64 s[8:9], s[6:7], 20
	s_add_u32 s8, s26, s8
	s_addc_u32 s9, s27, s9
	s_and_b64 s[10:11], vcc, exec
	s_cselect_b32 s7, s9, s13
	s_cselect_b32 s50, s8, s12
	s_ashr_i32 s1, s0, 31
	s_lshl_b64 s[10:11], s[0:1], 20
	s_add_u32 s10, s20, s10
	s_addc_u32 s11, s22, s11
	s_and_b64 s[18:19], vcc, exec
	s_cselect_b32 s1, s11, s15
	s_cselect_b32 s51, s10, s14
	s_add_u32 s12, s12, 0x80080
	s_addc_u32 s13, s13, 0
	s_add_u32 s52, s14, 0x100
	v_mov_b32_e32 v4, 0
	s_addc_u32 s53, s15, 0
	s_mov_b32 s54, -2
	v_mov_b32_e32 v5, v4
	v_mov_b32_e32 v6, v4
	v_mov_b32_e32 v7, v4
	v_mov_b32_e32 v8, v4
	v_mov_b32_e32 v9, v4
	v_mov_b32_e32 v10, v4
	v_mov_b32_e32 v11, v4
	v_mov_b32_e32 v20, v4
	v_mov_b32_e32 v21, v4
	v_mov_b32_e32 v22, v4
	v_mov_b32_e32 v23, v4
	v_mov_b32_e32 v24, v4
	v_mov_b32_e32 v25, v4
	v_mov_b32_e32 v26, v4
	v_mov_b32_e32 v27, v4
	v_mov_b32_e32 v36, v4
	v_mov_b32_e32 v37, v4
	v_mov_b32_e32 v38, v4
	v_mov_b32_e32 v39, v4
	v_mov_b32_e32 v40, v4
	v_mov_b32_e32 v41, v4
	v_mov_b32_e32 v42, v4
	v_mov_b32_e32 v43, v4
	v_mov_b32_e32 v52, v4
	v_mov_b32_e32 v53, v4
	v_mov_b32_e32 v54, v4
	v_mov_b32_e32 v55, v4
	v_mov_b32_e32 v56, v4
	v_mov_b32_e32 v57, v4
	v_mov_b32_e32 v58, v4
	v_mov_b32_e32 v59, v4
	v_mov_b32_e32 v12, v4
	v_mov_b32_e32 v13, v4
	v_mov_b32_e32 v14, v4
	v_mov_b32_e32 v15, v4
	v_mov_b32_e32 v16, v4
	v_mov_b32_e32 v17, v4
	v_mov_b32_e32 v18, v4
	v_mov_b32_e32 v19, v4
	v_mov_b32_e32 v28, v4
	v_mov_b32_e32 v29, v4
	v_mov_b32_e32 v30, v4
	v_mov_b32_e32 v31, v4
	v_mov_b32_e32 v32, v4
	v_mov_b32_e32 v33, v4
	v_mov_b32_e32 v34, v4
	v_mov_b32_e32 v35, v4
	v_mov_b32_e32 v44, v4
	v_mov_b32_e32 v45, v4
	v_mov_b32_e32 v46, v4
	v_mov_b32_e32 v47, v4
	v_mov_b32_e32 v48, v4
	v_mov_b32_e32 v49, v4
	v_mov_b32_e32 v50, v4
	v_mov_b32_e32 v51, v4
	v_mov_b32_e32 v60, v4
	v_mov_b32_e32 v61, v4
	v_mov_b32_e32 v62, v4
	v_mov_b32_e32 v63, v4
	v_mov_b32_e32 v64, v4
	v_mov_b32_e32 v65, v4
	v_mov_b32_e32 v66, v4
	v_mov_b32_e32 v67, v4
	v_mov_b32_e32 v76, v4
	v_mov_b32_e32 v77, v4
	v_mov_b32_e32 v78, v4
	v_mov_b32_e32 v79, v4
	v_mov_b32_e32 v80, v4
	v_mov_b32_e32 v81, v4
	v_mov_b32_e32 v82, v4
	v_mov_b32_e32 v83, v4
	v_mov_b32_e32 v100, v4
	v_mov_b32_e32 v101, v4
	v_mov_b32_e32 v102, v4
	v_mov_b32_e32 v103, v4
	v_mov_b32_e32 v104, v4
	v_mov_b32_e32 v105, v4
	v_mov_b32_e32 v106, v4
	v_mov_b32_e32 v107, v4
	v_mov_b32_e32 v116, v4
	v_mov_b32_e32 v117, v4
	v_mov_b32_e32 v118, v4
	v_mov_b32_e32 v119, v4
	v_mov_b32_e32 v120, v4
	v_mov_b32_e32 v121, v4
	v_mov_b32_e32 v122, v4
	v_mov_b32_e32 v123, v4
	v_mov_b32_e32 v132, v4
	v_mov_b32_e32 v133, v4
	v_mov_b32_e32 v134, v4
	v_mov_b32_e32 v135, v4
	v_mov_b32_e32 v136, v4
	v_mov_b32_e32 v137, v4
	v_mov_b32_e32 v138, v4
	v_mov_b32_e32 v139, v4
	v_mov_b32_e32 v92, v4
	v_mov_b32_e32 v93, v4
	v_mov_b32_e32 v94, v4
	v_mov_b32_e32 v95, v4
	v_mov_b32_e32 v96, v4
	v_mov_b32_e32 v97, v4
	v_mov_b32_e32 v98, v4
	v_mov_b32_e32 v99, v4
	v_mov_b32_e32 v108, v4
	v_mov_b32_e32 v109, v4
	v_mov_b32_e32 v110, v4
	v_mov_b32_e32 v111, v4
	v_mov_b32_e32 v112, v4
	v_mov_b32_e32 v113, v4
	v_mov_b32_e32 v114, v4
	v_mov_b32_e32 v115, v4
	v_mov_b32_e32 v124, v4
	v_mov_b32_e32 v125, v4
	v_mov_b32_e32 v126, v4
	v_mov_b32_e32 v127, v4
	v_mov_b32_e32 v128, v4
	v_mov_b32_e32 v129, v4
	v_mov_b32_e32 v130, v4
	v_mov_b32_e32 v131, v4
	v_mov_b32_e32 v140, v4
	v_mov_b32_e32 v141, v4
	v_mov_b32_e32 v142, v4
	v_mov_b32_e32 v143, v4
	v_mov_b32_e32 v144, v4
	v_mov_b32_e32 v145, v4
	v_mov_b32_e32 v146, v4
	v_mov_b32_e32 v147, v4
	.p2align	6
